# first XCD-local arriver at each grid barrier issues an early non-blocking buffer_wbl2 so the leader's release writeback has less to flush
# speedup vs baseline: 1.0044x; 1.0044x over previous
; __device__ __forceinline__ unsigned xb_ld(unsigned* p)              { return __hip_atomic_load(p, __ATOMIC_RELAXED, __HIP_MEMORY_SCOPE_AGENT); }
; __device__ __forceinline__ unsigned xb_add(unsigned* p, unsigned v) { return __hip_atomic_fetch_add(p, v, __ATOMIC_RELAXED, __HIP_MEMORY_SCOPE_AGENT); }
; #define XB_SPIN(cond, bar) do { unsigned _sp = 0; while (cond) { __builtin_amdgcn_s_sleep(1); \
;     if ((++_sp & 255u) == 0u) { if (xb_ld(&(bar)[XB_TMO])) break; if (_sp > XB_SPIN_CAP) { atomicAdd(&(bar)[XB_TMO], 1u); break; } } } } while (0)
; __device__ __forceinline__ void xcd_barrier(const XcdBarrier& b) {
;     ...
;         const unsigned old = xb_add(&bar[XB_XSUB(b.x)], 1u);
;         const unsigned gen = old / nloc;
;         if (old + 1u == (gen + 1u) * nloc) {
;             __builtin_amdgcn_fence(__ATOMIC_RELEASE, "agent");
;             asm volatile("s_waitcnt vmcnt(0)" ::: "memory");
;             const unsigned og = xb_add(&bar[XB_TOP], 1u);
;             const unsigned tg = og / nx;
;             if (og + 1u == (tg + 1u) * nx) xb_add(&bar[XB_TOPGEN], 1u);
;             else XB_SPIN(xb_ld(&bar[XB_TOPGEN]) == tg, bar);
;             __builtin_amdgcn_fence(__ATOMIC_ACQUIRE, "agent");
;             xb_add(&bar[XB_XGEN(b.x)], 1u);
;             asm volatile("s_waitcnt vmcnt(0)" ::: "memory");
;         } else {
;             XB_SPIN(xb_ld(&bar[XB_XGEN(b.x)]) == gen, bar);
.LBB0_109:
	s_or_b64 exec, exec, s[42:43]
	v_cvt_f32_u32_e32 v4, v2
	s_waitcnt vmcnt(0)
	v_readfirstlane_b32 s19, v3
	v_sub_u32_e32 v3, 0, v2
	v_rcp_iflag_f32_e32 v4, v4
	v_add_u32_e32 v5, s19, v1
	v_mul_f32_e32 v4, 0x4f7ffffe, v4
	v_cvt_u32_f32_e32 v4, v4
	v_mul_lo_u32 v1, v3, v4
	v_mul_hi_u32 v1, v4, v1
	v_add_u32_e32 v1, v4, v1
	v_mul_hi_u32 v1, v5, v1
	v_mul_lo_u32 v3, v1, v2
	v_sub_u32_e32 v3, v5, v3
	v_add_u32_e32 v4, 1, v1
	v_sub_u32_e32 v6, v3, v2
	v_cmp_ge_u32_e32 vcc, v3, v2
	s_nop 1
	v_cndmask_b32_e32 v1, v1, v4, vcc
	v_cndmask_b32_e32 v3, v3, v6, vcc
	v_add_u32_e32 v4, 1, v1
	v_cmp_ge_u32_e32 vcc, v3, v2
	v_add_u32_e32 v3, 1, v5
	s_nop 0
	v_cndmask_b32_e32 v1, v1, v4, vcc
	v_mul_lo_u32 v4, v2, v1
	v_add_u32_e32 v2, v4, v2
	v_cmp_ne_u32_e32 vcc, v3, v2
	s_and_saveexec_b64 s[20:21], vcc
	s_xor_b64 s[42:43], exec, s[20:21]
	s_cbranch_execz .LBB0_123
	v_cmp_eq_u32_e32 vcc, v5, v4
	s_cbranch_vccz .Lewb_skip_0
	buffer_wbl2 sc1
.Lewb_skip_0:
	v_readlane_b32 s0, v249, 33
	v_readlane_b32 s1, v249, 34
	s_waitcnt lgkmcnt(0)
	s_nop 3
	global_load_dword v0, v193, s[0:1] sc1
	s_waitcnt vmcnt(0)
	v_cmp_eq_u32_e32 vcc, v0, v1
	s_and_saveexec_b64 s[48:49], vcc
	s_cbranch_execz .LBB0_122
	s_mov_b32 s19, 1
	s_mov_b64 s[50:51], 0
	s_branch .LBB0_113

; __device__ __forceinline__ unsigned xb_ld(unsigned* p)              { return __hip_atomic_load(p, __ATOMIC_RELAXED, __HIP_MEMORY_SCOPE_AGENT); }
; __device__ __forceinline__ unsigned xb_add(unsigned* p, unsigned v) { return __hip_atomic_fetch_add(p, v, __ATOMIC_RELAXED, __HIP_MEMORY_SCOPE_AGENT); }
; #define XB_SPIN(cond, bar) do { unsigned _sp = 0; while (cond) { __builtin_amdgcn_s_sleep(1); \
;     if ((++_sp & 255u) == 0u) { if (xb_ld(&(bar)[XB_TMO])) break; if (_sp > XB_SPIN_CAP) { atomicAdd(&(bar)[XB_TMO], 1u); break; } } } } while (0)
; __device__ __forceinline__ void xcd_barrier(const XcdBarrier& b) {
;     ...
;         const unsigned old = xb_add(&bar[XB_XSUB(b.x)], 1u);
;         const unsigned gen = old / nloc;
;         if (old + 1u == (gen + 1u) * nloc) {
;             __builtin_amdgcn_fence(__ATOMIC_RELEASE, "agent");
;             asm volatile("s_waitcnt vmcnt(0)" ::: "memory");
;             const unsigned og = xb_add(&bar[XB_TOP], 1u);
;             const unsigned tg = og / nx;
;             if (og + 1u == (tg + 1u) * nx) xb_add(&bar[XB_TOPGEN], 1u);
;             else XB_SPIN(xb_ld(&bar[XB_TOPGEN]) == tg, bar);
;             __builtin_amdgcn_fence(__ATOMIC_ACQUIRE, "agent");
;             xb_add(&bar[XB_XGEN(b.x)], 1u);
;             asm volatile("s_waitcnt vmcnt(0)" ::: "memory");
;         } else {
;             XB_SPIN(xb_ld(&bar[XB_XGEN(b.x)]) == gen, bar);
.LBB0_279:
	s_or_b64 exec, exec, s[40:41]
	v_cvt_f32_u32_e32 v4, v2
	s_waitcnt vmcnt(0)
	v_readfirstlane_b32 s19, v3
	v_sub_u32_e32 v3, 0, v2
	v_rcp_iflag_f32_e32 v4, v4
	v_add_u32_e32 v5, s19, v1
	v_mul_f32_e32 v4, 0x4f7ffffe, v4
	v_cvt_u32_f32_e32 v4, v4
	v_mul_lo_u32 v1, v3, v4
	v_mul_hi_u32 v1, v4, v1
	v_add_u32_e32 v1, v4, v1
	v_mul_hi_u32 v1, v5, v1
	v_mul_lo_u32 v3, v1, v2
	v_sub_u32_e32 v3, v5, v3
	v_add_u32_e32 v4, 1, v1
	v_cmp_ge_u32_e32 vcc, v3, v2
	s_nop 1
	v_cndmask_b32_e32 v1, v1, v4, vcc
	v_sub_u32_e32 v4, v3, v2
	v_cndmask_b32_e32 v3, v3, v4, vcc
	v_add_u32_e32 v4, 1, v1
	v_cmp_ge_u32_e32 vcc, v3, v2
	v_add_u32_e32 v3, 1, v5
	s_nop 0
	v_cndmask_b32_e32 v1, v1, v4, vcc
	v_mul_lo_u32 v4, v2, v1
	v_add_u32_e32 v2, v4, v2
	v_cmp_ne_u32_e32 vcc, v3, v2
	s_and_saveexec_b64 s[20:21], vcc
	s_xor_b64 s[40:41], exec, s[20:21]
	s_cbranch_execz .LBB0_293
	v_cmp_eq_u32_e32 vcc, v5, v4
	s_cbranch_vccz .Lewb_skip_1
	buffer_wbl2 sc1
.Lewb_skip_1:
	v_readlane_b32 s0, v249, 33
	v_readlane_b32 s1, v249, 34
	s_waitcnt lgkmcnt(0)
	s_nop 3
	global_load_dword v0, v193, s[0:1] sc1
	s_waitcnt vmcnt(0)
	v_cmp_eq_u32_e32 vcc, v0, v1
	s_and_saveexec_b64 s[42:43], vcc
	s_cbranch_execz .LBB0_292
	s_mov_b32 s19, 1
	s_mov_b64 s[48:49], 0
	s_branch .LBB0_283

; __device__ __forceinline__ unsigned xb_ld(unsigned* p)              { return __hip_atomic_load(p, __ATOMIC_RELAXED, __HIP_MEMORY_SCOPE_AGENT); }
; #define XB_SPIN(cond, bar) do { unsigned _sp = 0; while (cond) { __builtin_amdgcn_s_sleep(1); \
;     if ((++_sp & 255u) == 0u) { if (xb_ld(&(bar)[XB_TMO])) break; if (_sp > XB_SPIN_CAP) { atomicAdd(&(bar)[XB_TMO], 1u); break; } } } } while (0)
; __device__ __forceinline__ void xcd_barrier(const XcdBarrier& b) {
;     ...
;         } else {
;             XB_SPIN(xb_ld(&bar[XB_XGEN(b.x)]) == gen, bar);
.Lewb_skip_2:
	v_readlane_b32 s0, v249, 33
	v_readlane_b32 s1, v249, 34
	s_waitcnt lgkmcnt(0)
	s_nop 3
	global_load_dword v0, v193, s[0:1] sc1
	s_waitcnt vmcnt(0)
	v_cmp_eq_u32_e32 vcc, v0, v1
	s_and_saveexec_b64 s[42:43], vcc
	s_cbranch_execz .LBB0_603
	s_mov_b32 s19, 1
	s_mov_b64 s[44:45], 0
	s_branch .LBB0_594

; __device__ __forceinline__ unsigned xb_ld(unsigned* p)              { return __hip_atomic_load(p, __ATOMIC_RELAXED, __HIP_MEMORY_SCOPE_AGENT); }
; __device__ __forceinline__ unsigned xb_add(unsigned* p, unsigned v) { return __hip_atomic_fetch_add(p, v, __ATOMIC_RELAXED, __HIP_MEMORY_SCOPE_AGENT); }
; #define XB_SPIN(cond, bar) do { unsigned _sp = 0; while (cond) { __builtin_amdgcn_s_sleep(1); \
;     if ((++_sp & 255u) == 0u) { if (xb_ld(&(bar)[XB_TMO])) break; if (_sp > XB_SPIN_CAP) { atomicAdd(&(bar)[XB_TMO], 1u); break; } } } } while (0)
; __device__ __forceinline__ void xcd_barrier(const XcdBarrier& b) {
;     ...
;         const unsigned old = xb_add(&bar[XB_XSUB(b.x)], 1u);
;         const unsigned gen = old / nloc;
;         if (old + 1u == (gen + 1u) * nloc) {
;             __builtin_amdgcn_fence(__ATOMIC_RELEASE, "agent");
;             asm volatile("s_waitcnt vmcnt(0)" ::: "memory");
;             const unsigned og = xb_add(&bar[XB_TOP], 1u);
;             const unsigned tg = og / nx;
;             if (og + 1u == (tg + 1u) * nx) xb_add(&bar[XB_TOPGEN], 1u);
;             else XB_SPIN(xb_ld(&bar[XB_TOPGEN]) == tg, bar);
;             __builtin_amdgcn_fence(__ATOMIC_ACQUIRE, "agent");
;             xb_add(&bar[XB_XGEN(b.x)], 1u);
;             asm volatile("s_waitcnt vmcnt(0)" ::: "memory");
;         } else {
;             XB_SPIN(xb_ld(&bar[XB_XGEN(b.x)]) == gen, bar);
.LBB0_716:
	s_or_b64 exec, exec, s[42:43]
	v_cvt_f32_u32_e32 v4, v2
	s_waitcnt vmcnt(0)
	v_readfirstlane_b32 s19, v3
	v_sub_u32_e32 v3, 0, v2
	v_rcp_iflag_f32_e32 v4, v4
	v_add_u32_e32 v5, s19, v1
	v_mul_f32_e32 v4, 0x4f7ffffe, v4
	v_cvt_u32_f32_e32 v4, v4
	v_mul_lo_u32 v1, v3, v4
	v_mul_hi_u32 v1, v4, v1
	v_add_u32_e32 v1, v4, v1
	v_mul_hi_u32 v1, v5, v1
	v_mul_lo_u32 v3, v1, v2
	v_sub_u32_e32 v3, v5, v3
	v_add_u32_e32 v4, 1, v1
	v_cmp_ge_u32_e32 vcc, v3, v2
	s_nop 1
	v_cndmask_b32_e32 v1, v1, v4, vcc
	v_sub_u32_e32 v4, v3, v2
	v_cndmask_b32_e32 v3, v3, v4, vcc
	v_add_u32_e32 v4, 1, v1
	v_cmp_ge_u32_e32 vcc, v3, v2
	v_add_u32_e32 v3, 1, v5
	s_nop 0
	v_cndmask_b32_e32 v1, v1, v4, vcc
	v_mul_lo_u32 v4, v2, v1
	v_add_u32_e32 v2, v4, v2
	v_cmp_ne_u32_e32 vcc, v3, v2
	s_and_saveexec_b64 s[20:21], vcc
	s_xor_b64 s[42:43], exec, s[20:21]
	s_cbranch_execz .LBB0_730
	v_cmp_eq_u32_e32 vcc, v5, v4
	s_cbranch_vccz .Lewb_skip_3
	buffer_wbl2 sc1
.Lewb_skip_3:
	v_readlane_b32 s0, v249, 33
	v_readlane_b32 s1, v249, 34
	s_waitcnt lgkmcnt(0)
	s_nop 3
	global_load_dword v0, v193, s[0:1] sc1
	s_waitcnt vmcnt(0)
	v_cmp_eq_u32_e32 vcc, v0, v1
	s_and_saveexec_b64 s[44:45], vcc
	s_cbranch_execz .LBB0_729
	s_mov_b32 s19, 1
	s_mov_b64 s[46:47], 0
	s_branch .LBB0_720
